# DIFF attention step 1: cross-half max (ds_bpermute result) consumed at the end of the step, mid-step wait lowered to lgkmcnt(1) so the LDS round trip is off the critical chain, on top of v18
# baseline (speedup 1.0000x reference)
.LBB0_681:
	v_add3_u32 v1, s21, v209, v213
	ds_read_b128 v[6:9], v1
	ds_read_b128 v[10:13], v1 offset:32
	ds_read_b128 v[112:115], v1 offset:64
	ds_read_b128 v[2:5], v1 offset:96
	s_mulk_i32 s31, 0x4800
	v_add_u32_e32 v132, s31, v223
	ds_read_b128 v[124:127], v132 offset:18496
	ds_read_b128 v[128:131], v132 offset:18528
	ds_read_b128 v[134:137], v132 offset:23104
	ds_read_b128 v[138:141], v132 offset:23136
	ds_read_b128 v[142:145], v132 offset:27712
	ds_read_b128 v[146:149], v132 offset:27744
	ds_read_b128 v[150:153], v132 offset:32320
	ds_read_b128 v[154:157], v132 offset:32352
	s_waitcnt lgkmcnt(11)
	v_mfma_f32_32x32x16_bf16 v[96:111], v[6:9], v[176:179], v[160:175]
	v_exp_f32_e32 v7, v16
	v_exp_f32_e32 v9, v17
	v_max_f32_e32 v1, v16, v17
	s_waitcnt lgkmcnt(10)
	v_mfma_f32_32x32x16_bf16 v[96:111], v[10:13], v[180:183], v[96:111]
	v_exp_f32_e32 v11, v18
	v_exp_f32_e32 v12, v19
	v_exp_f32_e32 v13, v20
	v_add_f32_e32 v8, v9, v7
	v_exp_f32_e32 v14, v21
	v_add_f32_e32 v8, v11, v8
	v_exp_f32_e32 v15, v22
	v_max3_f32 v1, v1, v18, v19
	v_add_f32_e32 v8, v12, v8
	v_exp_f32_e32 v16, v23
	v_max3_f32 v1, v1, v20, v21
	v_add_f32_e32 v8, v13, v8
	v_exp_f32_e32 v17, v24
	v_max3_f32 v1, v1, v22, v23
	v_add_f32_e32 v8, v14, v8
	v_exp_f32_e32 v18, v25
	v_max3_f32 v1, v1, v24, v25
	v_add_f32_e32 v8, v15, v8
	v_exp_f32_e32 v19, v26
	v_max3_f32 v1, v1, v26, v27
	v_add_f32_e32 v8, v16, v8
	v_exp_f32_e32 v20, v27
	v_max3_f32 v1, v1, v28, v29
	v_add_f32_e32 v8, v17, v8
	v_exp_f32_e32 v21, v28
	v_max3_f32 v1, v1, v30, v31
	v_add_f32_e32 v8, v18, v8
	v_exp_f32_e32 v22, v29
	ds_bpermute_b32 v133, v247, v1
	v_add_f32_e32 v8, v19, v8
	v_exp_f32_e32 v23, v30
	v_add_f32_e32 v8, v20, v8
	v_exp_f32_e32 v24, v31
	v_add_f32_e32 v8, v21, v8
	v_add_f32_e32 v8, v22, v8
	v_add_f32_e32 v8, v23, v8
	v_add_f32_e32 v8, v24, v8
	s_waitcnt lgkmcnt(1)
	v_mov_b32_e32 v210, v1
	v_add_f32_e32 v1, v216, v8
	v_cvt_pk_bf16_f32 v8, v21, v22
	v_cvt_pk_bf16_f32 v10, v7, v9
	v_cvt_pk_bf16_f32 v11, v11, v12
	v_cvt_pk_bf16_f32 v12, v13, v14
	v_cvt_pk_bf16_f32 v13, v15, v16
	v_cvt_pk_bf16_f32 v6, v17, v18
	v_cvt_pk_bf16_f32 v7, v19, v20
	v_mfma_f32_32x32x16_bf16 v[96:111], v[112:115], v[184:187], v[96:111]
	v_cvt_pk_bf16_f32 v9, v23, v24
	v_mfma_f32_32x32x16_bf16 v[32:47], v[124:127], v[10:13], v[32:47]
	v_mfma_f32_32x32x16_bf16 v[48:63], v[134:137], v[10:13], v[48:63]
	v_mfma_f32_32x32x16_bf16 v[48:63], v[138:141], v[6:9], v[48:63]
	v_mfma_f32_32x32x16_bf16 v[64:79], v[142:145], v[10:13], v[64:79]
	v_mfma_f32_32x32x16_bf16 v[64:79], v[146:149], v[6:9], v[64:79]
	v_mfma_f32_32x32x16_bf16 v[80:95], v[150:153], v[10:13], v[80:95]
	v_mfma_f32_32x32x16_bf16 v[32:47], v[128:131], v[6:9], v[32:47]
	v_mfma_f32_32x32x16_bf16 v[80:95], v[154:157], v[6:9], v[80:95]
	v_mfma_f32_32x32x16_bf16 v[16:31], v[2:5], v[188:191], v[96:111]
	s_waitcnt lgkmcnt(0)
	v_max_f32_e32 v2, v210, v133
	v_cmp_lt_f32_e32 vcc, s2, v2
	s_cbranch_vccz .LBB0_698
	v_max_f32_e32 v2, v2, v2
	v_max_f32_e32 v3, 0, v2
	v_exp_f32_e64 v2, -v3
	v_add_f32_e32 v6, v217, v3
	v_mul_f32_e32 v1, v2, v1
	s_nop 3
	v_pk_mul_f32 v[46:47], v[46:47], v[2:3] op_sel_hi:[1,0]
	v_pk_mul_f32 v[44:45], v[44:45], v[2:3] op_sel_hi:[1,0]
	v_pk_mul_f32 v[42:43], v[42:43], v[2:3] op_sel_hi:[1,0]
	v_pk_mul_f32 v[40:41], v[40:41], v[2:3] op_sel_hi:[1,0]
	v_pk_mul_f32 v[38:39], v[38:39], v[2:3] op_sel_hi:[1,0]
	v_pk_mul_f32 v[36:37], v[36:37], v[2:3] op_sel_hi:[1,0]
	v_pk_mul_f32 v[34:35], v[34:35], v[2:3] op_sel_hi:[1,0]
	v_pk_mul_f32 v[32:33], v[32:33], v[2:3] op_sel_hi:[1,0]
	v_pk_mul_f32 v[62:63], v[62:63], v[2:3] op_sel_hi:[1,0]
	v_pk_mul_f32 v[60:61], v[60:61], v[2:3] op_sel_hi:[1,0]
	v_pk_mul_f32 v[58:59], v[58:59], v[2:3] op_sel_hi:[1,0]
	v_pk_mul_f32 v[56:57], v[56:57], v[2:3] op_sel_hi:[1,0]
	v_pk_mul_f32 v[54:55], v[54:55], v[2:3] op_sel_hi:[1,0]
	v_pk_mul_f32 v[52:53], v[52:53], v[2:3] op_sel_hi:[1,0]
	v_pk_mul_f32 v[50:51], v[50:51], v[2:3] op_sel_hi:[1,0]
	v_pk_mul_f32 v[48:49], v[48:49], v[2:3] op_sel_hi:[1,0]
	v_pk_mul_f32 v[78:79], v[2:3], v[78:79] op_sel_hi:[0,1]
	v_pk_mul_f32 v[76:77], v[2:3], v[76:77] op_sel_hi:[0,1]
	v_pk_mul_f32 v[74:75], v[2:3], v[74:75] op_sel_hi:[0,1]
	v_pk_mul_f32 v[72:73], v[2:3], v[72:73] op_sel_hi:[0,1]
	v_pk_mul_f32 v[70:71], v[2:3], v[70:71] op_sel_hi:[0,1]
	v_pk_mul_f32 v[68:69], v[2:3], v[68:69] op_sel_hi:[0,1]
	v_pk_mul_f32 v[66:67], v[2:3], v[66:67] op_sel_hi:[0,1]
	v_pk_mul_f32 v[64:65], v[2:3], v[64:65] op_sel_hi:[0,1]
	v_pk_mul_f32 v[94:95], v[2:3], v[94:95] op_sel_hi:[0,1]
	v_pk_mul_f32 v[92:93], v[2:3], v[92:93] op_sel_hi:[0,1]
	v_pk_mul_f32 v[90:91], v[2:3], v[90:91] op_sel_hi:[0,1]
	v_pk_mul_f32 v[88:89], v[2:3], v[88:89] op_sel_hi:[0,1]
	v_pk_mul_f32 v[86:87], v[2:3], v[86:87] op_sel_hi:[0,1]
	v_pk_mul_f32 v[84:85], v[2:3], v[84:85] op_sel_hi:[0,1]
	v_pk_mul_f32 v[82:83], v[2:3], v[82:83] op_sel_hi:[0,1]
	v_pk_mul_f32 v[80:81], v[2:3], v[80:81] op_sel_hi:[0,1]
	v_sub_f32_e32 v16, v16, v3
	v_sub_f32_e32 v17, v17, v3
	v_sub_f32_e32 v18, v18, v3
	v_sub_f32_e32 v19, v19, v3
	v_sub_f32_e32 v20, v20, v3
	v_sub_f32_e32 v21, v21, v3
	v_sub_f32_e32 v22, v22, v3
	v_sub_f32_e32 v23, v23, v3
	v_sub_f32_e32 v24, v24, v3
	v_sub_f32_e32 v25, v25, v3
	v_sub_f32_e32 v26, v26, v3
	v_sub_f32_e32 v27, v27, v3
	v_sub_f32_e32 v28, v28, v3
	v_sub_f32_e32 v29, v29, v3
	v_sub_f32_e32 v30, v30, v3
	v_sub_f32_e32 v31, v31, v3
	v_sub_f32_e32 v160, v160, v3
	v_sub_f32_e32 v161, v161, v3
	v_sub_f32_e32 v162, v162, v3
	v_sub_f32_e32 v163, v163, v3
	v_sub_f32_e32 v164, v164, v3
	v_sub_f32_e32 v165, v165, v3
	v_sub_f32_e32 v166, v166, v3
	v_sub_f32_e32 v167, v167, v3
	v_sub_f32_e32 v168, v168, v3
	v_sub_f32_e32 v169, v169, v3
	v_sub_f32_e32 v170, v170, v3
	v_sub_f32_e32 v171, v171, v3
	v_sub_f32_e32 v172, v172, v3
	v_sub_f32_e32 v173, v173, v3
	v_sub_f32_e32 v174, v174, v3
	v_sub_f32_e32 v175, v175, v3
	s_cbranch_execz .LBB0_685
	s_branch .LBB0_686
